# P1 in-proj epilogue: all 32 output stores (q/k rope path and u/v plain path) made nontemporal, on top of P1 LDS tables + P2 pointer SALU
# baseline (speedup 1.0000x reference)
;     __device__ __forceinline__ void operator()(const f32x4 (&acc)[2][2][4][2], const Unit& u, int wr, int wc, int fr, int fq) const {
;     ...
;         const float* g = isK ? kg : qg; const float sc = isK ? 1.f : QK_C2;
;         bf16_t* base; int pitch;
;         if (isK) { base = KV + (size_t)row0 * 256 + wc * 64 + 8 * fq; pitch = 256; } else { base = MIX + (size_t)row0 * 1024 + (u.pn * 4 + wc) * 64 + 8 * fq; pitch = 1024; }
;         f32x4 gv[2][2];
; #pragma unroll
;         for (int bj = 0; bj < 2; ++bj)
; #pragma unroll
;             for (int n = 0; n < 2; ++n) gv[bj][n] = *(const f32x4*)(g + 32 * bj + 16 * n + 4 * fq) * sc;
;         const int rowt = u.pm * BM; const int t0 = rowt < ROWS_PROMPT ? (rowt & 4095) : ((rowt - ROWS_PROMPT) & 8191);
;         const int prow_base = (t0 >> 6) + wr;
; #pragma unroll
;         for (int ai = 0; ai < 2; ++ai) {
;             const int prow = prow_base + 2 * ai;
;             const f32x4 cr = *(const f32x4*)(cosT + prow * 16 + 4 * fq), sr = *(const f32x4*)(sinT + prow * 16 + 4 * fq);
; #pragma unroll
;             for (int m = 0; m < 4; ++m) {
;                 const int pcol = 16 * m + fr;
;                 const f32x4 cc = *(const f32x4*)(cosT + pcol * 16 + 4 * fq), sn = *(const f32x4*)(sinT + pcol * 16 + 4 * fq);
;                 float ss = 0.f;
; #pragma unroll
;                 for (int bj = 0; bj < 2; ++bj)
; #pragma unroll
;                     for (int n = 0; n < 2; ++n) { const f32x4 x = acc[ai][bj][m][n]; ss += (x[0] * x[0] + x[1] * x[1]) + (x[2] * x[2] + x[3] * x[3]); }
;                 ss += __shfl_xor(ss, 16); ss += __shfl_xor(ss, 32);
;                 const float rstd = __builtin_amdgcn_rsqf(ss * (1.0f / 64.0f) + RMS_EPS);
;                 bf16_t* rowp = base + (size_t)(ai * HALF + m * 16) * pitch;
; #pragma unroll
;                 for (int bj = 0; bj < 2; ++bj) { const f32x4 c = bj == 0 ? cr : cc, s = bj == 0 ? sr : sn;
;                     const f32x4 y0 = acc[ai][bj][m][0] * rstd * gv[bj][0], y1 = acc[ai][bj][m][1] * rstd * gv[bj][1];
;                     const f32x4 o0 = y0 * c - y1 * s, o1 = y1 * c + y0 * s;
;                     u32x4 w; w.x = cvt_pk_bf16(o0[0], o0[1]); w.y = cvt_pk_bf16(o0[2], o0[3]); w.z = cvt_pk_bf16(o1[0], o1[1]); w.w = cvt_pk_bf16(o1[2], o1[3]);
;                     *(u32x4*)(rowp + bj * 32) = w; }
.LBB0_255:
	s_and_b64 s[0:1], s[30:31], exec
	s_cselect_b32 s1, s55, s53
	s_cselect_b32 s0, s54, s52
	global_load_dwordx4 v[180:183], v199, s[0:1]
	global_load_dwordx4 v[184:187], v199, s[0:1] offset:64
	s_cmpk_lt_i32 s12, 0x80
	global_load_dwordx4 v[210:213], v199, s[0:1] offset:128
	global_load_dwordx4 v[214:217], v199, s[0:1] offset:192
	s_movk_i32 s0, 0xf00
	s_cselect_b32 s0, s0, 0x1f00
	s_and_b32 s0, s0, s19
	s_lshr_b32 s0, s0, 6
	s_add_i32 s0, s0, s37
	s_lshl_b32 s12, s0, 6
	v_lshl_add_u64 v[194:195], v[152:153], 0, s[12:13]
	v_lshl_add_u64 v[196:197], v[150:151], 0, s[12:13]
	global_load_dwordx4 v[130:133], v[194:195], off
	global_load_dwordx4 v[134:137], v[196:197], off
	global_load_dwordx4 v[240:243], v[194:195], off offset:128
	global_load_dwordx4 v[244:247], v[196:197], off offset:128
	global_load_dwordx4 v[218:221], v[154:155], off
	global_load_dwordx4 v[222:225], v[156:157], off
	v_pk_mul_f32 v[188:189], v[128:129], v[128:129]
	v_pk_mul_f32 v[190:191], v[126:127], v[126:127]
	v_pk_mul_f32 v[192:193], v[124:125], v[124:125]
	v_pk_mul_f32 v[226:227], v[122:123], v[122:123]
	v_pk_mov_b32 v[230:231], v[190:191], v[188:189] op_sel:[1,0]
	v_mov_b32_e32 v191, v189
	v_pk_mov_b32 v[188:189], v[226:227], v[192:193] op_sel:[1,0]
	v_mov_b32_e32 v227, v193
	v_mul_f32_e32 v146, v119, v119
	v_mul_f32_e32 v228, v121, v121
	v_pk_add_f32 v[190:191], v[230:231], v[190:191]
	v_pk_add_f32 v[188:189], v[188:189], v[226:227]
	v_and_b32_e32 v207, 64, v206
	v_mul_f32_e32 v209, v110, v110
	v_mul_f32_e32 v232, v111, v111
	v_mul_f32_e32 v233, v112, v112
	v_mul_f32_e32 v234, v113, v113
	v_pk_fma_f32 v[192:193], v[118:119], v[118:119], v[146:147] op_sel_hi:[1,1,0]
	v_pk_fma_f32 v[228:229], v[120:121], v[120:121], v[228:229] op_sel_hi:[1,1,0]
	v_pk_add_f32 v[190:191], v[190:191], v[190:191] op_sel:[0,1] op_sel_hi:[1,0]
	v_pk_add_f32 v[188:189], v[188:189], v[188:189] op_sel:[0,1] op_sel_hi:[1,0]
	v_xor_b32_e32 v177, 16, v206
	v_add_u32_e32 v207, 64, v207
	v_mov_b32_e32 v193, v233
	v_mov_b32_e32 v229, v234
	v_mov_b32_e32 v191, v209
	v_mov_b32_e32 v189, v232
	v_cmp_lt_i32_e32 vcc, v177, v207
	v_pk_add_f32 v[192:193], v[192:193], v[228:229]
	v_pk_add_f32 v[188:189], v[190:191], v[188:189]
	v_cndmask_b32_e32 v146, v206, v177, vcc
	v_pk_add_f32 v[188:189], v[188:189], v[192:193]
	v_lshlrev_b32_e32 v177, 2, v146
	v_add_f32_e32 v146, v188, v189
	ds_bpermute_b32 v188, v177, v146
	v_xor_b32_e32 v189, 32, v206
	v_cmp_lt_i32_e32 vcc, v189, v207
	v_mul_f32_e32 v209, v91, v91
	s_lshl_b32 s12, s28, 5
	v_cndmask_b32_e32 v189, v206, v189, vcc
	v_lshlrev_b32_e32 v207, 2, v189
	s_waitcnt lgkmcnt(0)
	v_add_f32_e32 v146, v146, v188
	ds_bpermute_b32 v188, v207, v146
	s_mul_i32 s0, s28, 0xa0
	s_mov_b32 s1, s13
	s_mov_b64 s[28:29], 0
	s_waitcnt lgkmcnt(0)
	v_add_f32_e32 v146, v146, v188
	v_fmamk_f32 v146, v146, 0x3c800000, v200
	v_rsq_f32_e32 v226, v146
	v_cndmask_b32_e64 v188, v205, 1.0, s[30:31]
	v_lshlrev_b32_e32 v146, 1, v148
	v_lshl_add_u64 v[228:229], v[178:179], 0, v[146:147]
	v_pk_mul_f32 v[234:235], v[122:123], v[226:227] op_sel_hi:[1,0]
	v_pk_mul_f32 v[236:237], v[124:125], v[226:227] op_sel_hi:[1,0]
	v_pk_mul_f32 v[230:231], v[128:129], v[226:227] op_sel_hi:[1,0]
	v_pk_mul_f32 v[232:233], v[126:127], v[226:227] op_sel_hi:[1,0]
	v_mul_f32_e32 v146, v90, v90
	s_waitcnt vmcnt(0)
	v_pk_mul_f32 v[178:179], v[188:189], v[182:183] op_sel_hi:[0,1]
	v_pk_mul_f32 v[182:183], v[188:189], v[186:187] op_sel_hi:[0,1]
	v_pk_mul_f32 v[184:185], v[188:189], v[184:185] op_sel_hi:[0,1]
	v_pk_mul_f32 v[190:191], v[188:189], v[180:181] op_sel_hi:[0,1]
	v_pk_mul_f32 v[180:181], v[188:189], v[212:213] op_sel_hi:[0,1]
	v_pk_mul_f32 v[192:193], v[188:189], v[210:211] op_sel_hi:[0,1]
	v_pk_mul_f32 v[186:187], v[188:189], v[216:217] op_sel_hi:[0,1]
	v_pk_mul_f32 v[188:189], v[188:189], v[214:215] op_sel_hi:[0,1]
	v_pk_mul_f32 v[214:215], v[182:183], v[236:237]
	v_pk_mul_f32 v[216:217], v[184:185], v[234:235]
	v_pk_mul_f32 v[210:211], v[190:191], v[232:233]
	v_pk_mul_f32 v[212:213], v[178:179], v[230:231]
	v_pk_mul_f32 v[230:231], v[130:131], v[216:217]
	v_pk_mul_f32 v[232:233], v[132:133], v[214:215]
	v_pk_mul_f32 v[216:217], v[134:135], v[216:217]
	v_pk_mul_f32 v[214:215], v[136:137], v[214:215]
	v_pk_fma_f32 v[232:233], v[136:137], v[212:213], v[232:233] neg_lo:[0,0,1] neg_hi:[0,0,1]
	v_pk_fma_f32 v[214:215], v[132:133], v[212:213], v[214:215]
	v_pk_fma_f32 v[212:213], v[130:131], v[210:211], v[216:217]
	v_pk_fma_f32 v[230:231], v[134:135], v[210:211], v[230:231] neg_lo:[0,0,1] neg_hi:[0,0,1]
	v_pk_mul_f32 v[216:217], v[112:113], v[226:227] op_sel_hi:[1,0]
	v_cvt_pk_bf16_f32 v210, v230, v231
	v_cvt_pk_bf16_f32 v211, v232, v233
	v_cvt_pk_bf16_f32 v212, v212, v213
	v_cvt_pk_bf16_f32 v213, v214, v215
	v_pk_mul_f32 v[214:215], v[110:111], v[226:227] op_sel_hi:[1,0]
	global_store_dwordx4 v[228:229], v[210:213], off nt
	v_pk_mul_f32 v[214:215], v[188:189], v[214:215]
	v_pk_mul_f32 v[216:217], v[186:187], v[216:217]
	v_pk_mul_f32 v[212:213], v[118:119], v[226:227] op_sel_hi:[1,0]
	v_pk_mul_f32 v[210:211], v[120:121], v[226:227] op_sel_hi:[1,0]
	v_pk_mul_f32 v[212:213], v[192:193], v[212:213]
	v_pk_mul_f32 v[226:227], v[222:223], v[214:215]
	v_pk_mul_f32 v[214:215], v[218:219], v[214:215]
	v_pk_mul_f32 v[210:211], v[180:181], v[210:211]
	v_pk_mul_f32 v[230:231], v[224:225], v[216:217]
	v_pk_fma_f32 v[226:227], v[218:219], v[212:213], v[226:227] neg_lo:[0,0,1] neg_hi:[0,0,1]
	v_pk_mul_f32 v[216:217], v[220:221], v[216:217]
	v_pk_fma_f32 v[212:213], v[222:223], v[212:213], v[214:215]
	v_pk_fma_f32 v[230:231], v[220:221], v[210:211], v[230:231] neg_lo:[0,0,1] neg_hi:[0,0,1]
; __device__ __forceinline__ unsigned cvt_pk_bf16(float lo, float hi) { unsigned r; asm volatile("v_cvt_pk_bf16_f32 %0, %1, %2" : "=v"(r) : "v"(lo), "v"(hi)); return r; }
;     __device__ __forceinline__ void operator()(const f32x4 (&acc)[2][2][4][2], const Unit& u, int wr, int wc, int fr, int fq) const {
;     ...
;             for (int m = 0; m < 4; ++m) {
;                 const int pcol = 16 * m + fr;
;                 const f32x4 cc = *(const f32x4*)(cosT + pcol * 16 + 4 * fq), sn = *(const f32x4*)(sinT + pcol * 16 + 4 * fq);
;                 float ss = 0.f;
; #pragma unroll
;                 for (int bj = 0; bj < 2; ++bj)
; #pragma unroll
;                     for (int n = 0; n < 2; ++n) { const f32x4 x = acc[ai][bj][m][n]; ss += (x[0] * x[0] + x[1] * x[1]) + (x[2] * x[2] + x[3] * x[3]); }
;                 ss += __shfl_xor(ss, 16); ss += __shfl_xor(ss, 32);
;                 const float rstd = __builtin_amdgcn_rsqf(ss * (1.0f / 64.0f) + RMS_EPS);
;                 bf16_t* rowp = base + (size_t)(ai * HALF + m * 16) * pitch;
; #pragma unroll
;                 for (int bj = 0; bj < 2; ++bj) { const f32x4 c = bj == 0 ? cr : cc, s = bj == 0 ? sr : sn;
;                     const f32x4 y0 = acc[ai][bj][m][0] * rstd * gv[bj][0], y1 = acc[ai][bj][m][1] * rstd * gv[bj][1];
;                     const f32x4 o0 = y0 * c - y1 * s, o1 = y1 * c + y0 * s;
;                     u32x4 w; w.x = cvt_pk_bf16(o0[0], o0[1]); w.y = cvt_pk_bf16(o0[2], o0[3]); w.z = cvt_pk_bf16(o1[0], o1[1]); w.w = cvt_pk_bf16(o1[2], o1[3]);
;                     *(u32x4*)(rowp + bj * 32) = w; }
	v_pk_fma_f32 v[216:217], v[224:225], v[210:211], v[216:217]
	v_cvt_pk_bf16_f32 v210, v226, v227
	v_cvt_pk_bf16_f32 v211, v230, v231
	v_cvt_pk_bf16_f32 v212, v212, v213
	v_pk_mul_f32 v[218:219], v[116:117], v[116:117]
	v_cvt_pk_bf16_f32 v213, v216, v217
	global_store_dwordx4 v[228:229], v[210:213], off offset:64 nt
	v_subrev_u32_e32 v252, s98, v160
	v_bfe_u32 v253, v252, 13, 1
	v_and_b32_e32 v252, 0xfff, v252
	v_lshl_or_b32 v252, v253, 12, v252
	v_add_u32_e32 v252, 0x20800, v252
	ds_read_b128 v[210:213], v252
	s_nop 0
	v_subrev_u32_e32 v252, s98, v158
	v_bfe_u32 v253, v252, 13, 1
	v_and_b32_e32 v252, 0xfff, v252
	v_lshl_or_b32 v252, v253, 12, v252
	v_add_u32_e32 v252, 0x20800, v252
	ds_read_b128 v[214:217], v252
	v_pk_mul_f32 v[220:221], v[114:115], v[114:115]
	s_nop 0
	v_pk_mov_b32 v[222:223], v[220:221], v[218:219] op_sel:[1,0]
	v_mov_b32_e32 v221, v219
	v_pk_add_f32 v[218:219], v[222:223], v[220:221]
	v_pk_mul_f32 v[220:221], v[108:109], v[108:109]
	v_pk_mul_f32 v[222:223], v[106:107], v[106:107]
	v_pk_add_f32 v[218:219], v[218:219], v[218:219] op_sel:[0,1] op_sel_hi:[1,0]
	v_pk_mov_b32 v[224:225], v[222:223], v[220:221] op_sel:[1,0]
	v_mov_b32_e32 v223, v221
	v_pk_add_f32 v[220:221], v[224:225], v[222:223]
	v_mov_b32_e32 v219, v146
	v_pk_add_f32 v[220:221], v[220:221], v[220:221] op_sel:[0,1] op_sel_hi:[1,0]
	v_mul_f32_e32 v146, v99, v99
	v_mov_b32_e32 v221, v209
	v_mul_f32_e32 v222, v92, v92
	v_pk_add_f32 v[218:219], v[218:219], v[220:221]
	v_pk_fma_f32 v[220:221], v[98:99], v[98:99], v[146:147] op_sel_hi:[1,1,0]
	v_mul_f32_e32 v146, v101, v101
	v_mul_f32_e32 v224, v93, v93
	v_mov_b32_e32 v221, v222
	v_pk_fma_f32 v[222:223], v[100:101], v[100:101], v[146:147] op_sel_hi:[1,1,0]
	s_nop 0
	v_mov_b32_e32 v223, v224
	v_pk_add_f32 v[220:221], v[220:221], v[222:223]
	v_lshl_add_u64 v[222:223], v[228:229], 0, s[12:13]
	v_pk_add_f32 v[218:219], v[218:219], v[220:221]
	s_nop 0
	v_add_f32_e32 v146, v218, v219
	ds_bpermute_b32 v209, v177, v146
	s_waitcnt lgkmcnt(0)
	v_add_f32_e32 v146, v146, v209
	ds_bpermute_b32 v209, v207, v146
	s_waitcnt lgkmcnt(0)
	v_add_f32_e32 v146, v146, v209
	v_fmamk_f32 v146, v146, 0x3c800000, v200
	v_rsq_f32_e32 v146, v146
	v_mul_f32_e32 v209, v75, v75
	v_pk_mul_f32 v[224:225], v[106:107], v[146:147] op_sel_hi:[1,0]
	v_pk_mul_f32 v[226:227], v[108:109], v[146:147] op_sel_hi:[1,0]
	v_pk_mul_f32 v[218:219], v[116:117], v[146:147] op_sel_hi:[1,0]
	v_pk_mul_f32 v[220:221], v[114:115], v[146:147] op_sel_hi:[1,0]
	v_pk_mul_f32 v[226:227], v[182:183], v[226:227]
	v_pk_mul_f32 v[224:225], v[184:185], v[224:225]
	v_pk_mul_f32 v[220:221], v[190:191], v[220:221]
	v_pk_mul_f32 v[218:219], v[178:179], v[218:219]
	v_pk_mul_f32 v[228:229], v[130:131], v[224:225]
	v_pk_mul_f32 v[230:231], v[132:133], v[226:227]
	v_pk_mul_f32 v[224:225], v[134:135], v[224:225]
	v_pk_mul_f32 v[226:227], v[136:137], v[226:227]
	v_pk_fma_f32 v[228:229], v[134:135], v[220:221], v[228:229] neg_lo:[0,0,1] neg_hi:[0,0,1]
	v_pk_fma_f32 v[226:227], v[132:133], v[218:219], v[226:227]
	v_pk_fma_f32 v[220:221], v[130:131], v[220:221], v[224:225]
	v_pk_fma_f32 v[230:231], v[136:137], v[218:219], v[230:231] neg_lo:[0,0,1] neg_hi:[0,0,1]
	v_cvt_pk_bf16_f32 v218, v228, v229
	v_pk_mul_f32 v[224:225], v[90:91], v[146:147] op_sel_hi:[1,0]
	v_cvt_pk_bf16_f32 v219, v230, v231
	v_cvt_pk_bf16_f32 v220, v220, v221
	v_cvt_pk_bf16_f32 v221, v226, v227
	v_pk_mul_f32 v[226:227], v[92:93], v[146:147] op_sel_hi:[1,0]
	global_store_dwordx4 v[222:223], v[218:221], off nt
	v_pk_mul_f32 v[226:227], v[186:187], v[226:227]
	v_pk_mul_f32 v[224:225], v[188:189], v[224:225]
	v_pk_mul_f32 v[218:219], v[100:101], v[146:147] op_sel_hi:[1,0]
	v_pk_mul_f32 v[220:221], v[98:99], v[146:147] op_sel_hi:[1,0]
	v_pk_mul_f32 v[218:219], v[180:181], v[218:219]
	v_pk_mul_f32 v[220:221], v[192:193], v[220:221]
	v_mul_f32_e32 v146, v74, v74
	s_waitcnt lgkmcnt(0)
	v_pk_mul_f32 v[228:229], v[210:211], v[224:225]
	v_pk_mul_f32 v[230:231], v[212:213], v[226:227]
	s_waitcnt lgkmcnt(0)
	v_pk_fma_f32 v[228:229], v[214:215], v[220:221], v[228:229] neg_lo:[0,0,1] neg_hi:[0,0,1]
	v_pk_fma_f32 v[230:231], v[216:217], v[218:219], v[230:231] neg_lo:[0,0,1] neg_hi:[0,0,1]
	v_pk_mul_f32 v[214:215], v[214:215], v[224:225]
	v_pk_mul_f32 v[216:217], v[216:217], v[226:227]
	s_nop 0
	v_pk_fma_f32 v[216:217], v[212:213], v[218:219], v[216:217]
	v_pk_fma_f32 v[212:213], v[210:211], v[220:221], v[214:215]
	v_cvt_pk_bf16_f32 v210, v228, v229
	v_cvt_pk_bf16_f32 v211, v230, v231
	v_pk_mul_f32 v[218:219], v[104:105], v[104:105]
	v_cvt_pk_bf16_f32 v212, v212, v213
	v_cvt_pk_bf16_f32 v213, v216, v217
	global_store_dwordx4 v[222:223], v[210:213], off offset:64 nt
	v_subrev_u32_e32 v252, s98, v164
	v_bfe_u32 v253, v252, 13, 1
	v_and_b32_e32 v252, 0xfff, v252
	v_lshl_or_b32 v252, v253, 12, v252
	v_add_u32_e32 v252, 0x20800, v252
	ds_read_b128 v[210:213], v252
	s_nop 0
	v_subrev_u32_e32 v252, s98, v162
	v_bfe_u32 v253, v252, 13, 1
	v_and_b32_e32 v252, 0xfff, v252
	v_lshl_or_b32 v252, v253, 12, v252
	v_add_u32_e32 v252, 0x20800, v252
	ds_read_b128 v[214:217], v252
	v_pk_mul_f32 v[220:221], v[102:103], v[102:103]
	v_lshl_add_u64 v[222:223], v[222:223], 0, s[12:13]
	v_pk_mov_b32 v[224:225], v[220:221], v[218:219] op_sel:[1,0]
	v_mov_b32_e32 v221, v219
	v_pk_add_f32 v[218:219], v[224:225], v[220:221]
	v_pk_mul_f32 v[220:221], v[96:97], v[96:97]
	v_pk_mul_f32 v[224:225], v[94:95], v[94:95]
	v_pk_add_f32 v[218:219], v[218:219], v[218:219] op_sel:[0,1] op_sel_hi:[1,0]
	v_pk_mov_b32 v[226:227], v[224:225], v[220:221] op_sel:[1,0]
	v_mov_b32_e32 v225, v221
	v_pk_add_f32 v[220:221], v[226:227], v[224:225]
	v_mov_b32_e32 v219, v146
	v_pk_add_f32 v[220:221], v[220:221], v[220:221] op_sel:[0,1] op_sel_hi:[1,0]
	v_mul_f32_e32 v146, v83, v83
	v_mov_b32_e32 v221, v209
	v_mul_f32_e32 v224, v76, v76
	v_pk_add_f32 v[218:219], v[218:219], v[220:221]
	v_pk_fma_f32 v[220:221], v[82:83], v[82:83], v[146:147] op_sel_hi:[1,1,0]
	v_mul_f32_e32 v146, v85, v85
	v_mul_f32_e32 v226, v77, v77
	v_mov_b32_e32 v221, v224
	v_pk_fma_f32 v[224:225], v[84:85], v[84:85], v[146:147] op_sel_hi:[1,1,0]
	s_nop 0
	v_mov_b32_e32 v225, v226
	v_pk_add_f32 v[220:221], v[220:221], v[224:225]
	s_nop 0
	v_pk_add_f32 v[218:219], v[218:219], v[220:221]
	s_nop 0
	v_add_f32_e32 v146, v218, v219
	ds_bpermute_b32 v209, v177, v146
	s_waitcnt lgkmcnt(0)
; __device__ __forceinline__ unsigned cvt_pk_bf16(float lo, float hi) { unsigned r; asm volatile("v_cvt_pk_bf16_f32 %0, %1, %2" : "=v"(r) : "v"(lo), "v"(hi)); return r; }
;     __device__ __forceinline__ void operator()(const f32x4 (&acc)[2][2][4][2], const Unit& u, int wr, int wc, int fr, int fq) const {
;     ...
;             for (int m = 0; m < 4; ++m) {
;                 const int pcol = 16 * m + fr;
;                 const f32x4 cc = *(const f32x4*)(cosT + pcol * 16 + 4 * fq), sn = *(const f32x4*)(sinT + pcol * 16 + 4 * fq);
;                 float ss = 0.f;
; #pragma unroll
;                 for (int bj = 0; bj < 2; ++bj)
; #pragma unroll
;                     for (int n = 0; n < 2; ++n) { const f32x4 x = acc[ai][bj][m][n]; ss += (x[0] * x[0] + x[1] * x[1]) + (x[2] * x[2] + x[3] * x[3]); }
;                 ss += __shfl_xor(ss, 16); ss += __shfl_xor(ss, 32);
;                 const float rstd = __builtin_amdgcn_rsqf(ss * (1.0f / 64.0f) + RMS_EPS);
;                 bf16_t* rowp = base + (size_t)(ai * HALF + m * 16) * pitch;
; #pragma unroll
;                 for (int bj = 0; bj < 2; ++bj) { const f32x4 c = bj == 0 ? cr : cc, s = bj == 0 ? sr : sn;
;                     const f32x4 y0 = acc[ai][bj][m][0] * rstd * gv[bj][0], y1 = acc[ai][bj][m][1] * rstd * gv[bj][1];
;                     const f32x4 o0 = y0 * c - y1 * s, o1 = y1 * c + y0 * s;
;                     u32x4 w; w.x = cvt_pk_bf16(o0[0], o0[1]); w.y = cvt_pk_bf16(o0[2], o0[3]); w.z = cvt_pk_bf16(o1[0], o1[1]); w.w = cvt_pk_bf16(o1[2], o1[3]);
;                     *(u32x4*)(rowp + bj * 32) = w; }
	v_add_f32_e32 v146, v146, v209
	ds_bpermute_b32 v209, v207, v146
	s_waitcnt lgkmcnt(0)
	v_add_f32_e32 v146, v146, v209
	v_fmamk_f32 v146, v146, 0x3c800000, v200
	v_rsq_f32_e32 v146, v146
	v_mul_f32_e32 v209, v67, v67
	v_pk_mul_f32 v[224:225], v[94:95], v[146:147] op_sel_hi:[1,0]
	v_pk_mul_f32 v[226:227], v[96:97], v[146:147] op_sel_hi:[1,0]
	v_pk_mul_f32 v[218:219], v[104:105], v[146:147] op_sel_hi:[1,0]
	v_pk_mul_f32 v[220:221], v[102:103], v[146:147] op_sel_hi:[1,0]
	v_pk_mul_f32 v[226:227], v[182:183], v[226:227]
	v_pk_mul_f32 v[224:225], v[184:185], v[224:225]
	v_pk_mul_f32 v[220:221], v[190:191], v[220:221]
	v_pk_mul_f32 v[218:219], v[178:179], v[218:219]
	v_pk_mul_f32 v[228:229], v[130:131], v[224:225]
	v_pk_mul_f32 v[230:231], v[132:133], v[226:227]
	v_pk_mul_f32 v[224:225], v[134:135], v[224:225]
	v_pk_mul_f32 v[226:227], v[136:137], v[226:227]
	v_pk_fma_f32 v[228:229], v[134:135], v[220:221], v[228:229] neg_lo:[0,0,1] neg_hi:[0,0,1]
	v_pk_fma_f32 v[226:227], v[132:133], v[218:219], v[226:227]
	v_pk_fma_f32 v[220:221], v[130:131], v[220:221], v[224:225]
	v_pk_fma_f32 v[230:231], v[136:137], v[218:219], v[230:231] neg_lo:[0,0,1] neg_hi:[0,0,1]
	v_cvt_pk_bf16_f32 v218, v228, v229
	v_pk_mul_f32 v[224:225], v[74:75], v[146:147] op_sel_hi:[1,0]
	v_cvt_pk_bf16_f32 v219, v230, v231
	v_cvt_pk_bf16_f32 v220, v220, v221
	v_cvt_pk_bf16_f32 v221, v226, v227
	v_pk_mul_f32 v[226:227], v[76:77], v[146:147] op_sel_hi:[1,0]
	global_store_dwordx4 v[222:223], v[218:221], off nt
	v_pk_mul_f32 v[226:227], v[186:187], v[226:227]
	v_pk_mul_f32 v[224:225], v[188:189], v[224:225]
	v_pk_mul_f32 v[218:219], v[84:85], v[146:147] op_sel_hi:[1,0]
	v_pk_mul_f32 v[220:221], v[82:83], v[146:147] op_sel_hi:[1,0]
	v_pk_mul_f32 v[218:219], v[180:181], v[218:219]
	v_pk_mul_f32 v[220:221], v[192:193], v[220:221]
	v_mul_f32_e32 v146, v66, v66
	s_waitcnt lgkmcnt(0)
	v_pk_mul_f32 v[228:229], v[210:211], v[224:225]
	v_pk_mul_f32 v[230:231], v[212:213], v[226:227]
	s_waitcnt lgkmcnt(0)
	v_pk_fma_f32 v[228:229], v[214:215], v[220:221], v[228:229] neg_lo:[0,0,1] neg_hi:[0,0,1]
	v_pk_fma_f32 v[230:231], v[216:217], v[218:219], v[230:231] neg_lo:[0,0,1] neg_hi:[0,0,1]
	v_pk_mul_f32 v[214:215], v[214:215], v[224:225]
	v_pk_mul_f32 v[216:217], v[216:217], v[226:227]
	s_nop 0
	v_pk_fma_f32 v[216:217], v[212:213], v[218:219], v[216:217]
	v_pk_fma_f32 v[212:213], v[210:211], v[220:221], v[214:215]
	v_cvt_pk_bf16_f32 v210, v228, v229
	v_cvt_pk_bf16_f32 v211, v230, v231
	v_pk_mul_f32 v[218:219], v[88:89], v[88:89]
	v_cvt_pk_bf16_f32 v212, v212, v213
	v_cvt_pk_bf16_f32 v213, v216, v217
	global_store_dwordx4 v[222:223], v[210:213], off offset:64 nt
	v_subrev_u32_e32 v252, s98, v168
	v_bfe_u32 v253, v252, 13, 1
	v_and_b32_e32 v252, 0xfff, v252
	v_lshl_or_b32 v252, v253, 12, v252
	v_add_u32_e32 v252, 0x20800, v252
	ds_read_b128 v[210:213], v252
	s_nop 0
	v_subrev_u32_e32 v252, s98, v166
	v_bfe_u32 v253, v252, 13, 1
	v_and_b32_e32 v252, 0xfff, v252
	v_lshl_or_b32 v252, v253, 12, v252
	v_add_u32_e32 v252, 0x20800, v252
	ds_read_b128 v[214:217], v252
	v_pk_mul_f32 v[220:221], v[86:87], v[86:87]
	s_nop 0
	v_pk_mov_b32 v[224:225], v[220:221], v[218:219] op_sel:[1,0]
	v_mov_b32_e32 v221, v219
	v_pk_add_f32 v[218:219], v[224:225], v[220:221]
	v_pk_mul_f32 v[220:221], v[80:81], v[80:81]
	v_pk_mul_f32 v[224:225], v[78:79], v[78:79]
	v_pk_add_f32 v[218:219], v[218:219], v[218:219] op_sel:[0,1] op_sel_hi:[1,0]
	v_pk_mov_b32 v[226:227], v[224:225], v[220:221] op_sel:[1,0]
	v_mov_b32_e32 v225, v221
	v_pk_add_f32 v[220:221], v[226:227], v[224:225]
	v_mov_b32_e32 v219, v146
	v_pk_add_f32 v[220:221], v[220:221], v[220:221] op_sel:[0,1] op_sel_hi:[1,0]
	v_mul_f32_e32 v146, v71, v71
	v_mov_b32_e32 v221, v209
	v_mul_f32_e32 v224, v68, v68
	v_pk_add_f32 v[218:219], v[218:219], v[220:221]
	v_pk_fma_f32 v[220:221], v[70:71], v[70:71], v[146:147] op_sel_hi:[1,1,0]
	v_mul_f32_e32 v146, v73, v73
	v_mul_f32_e32 v226, v69, v69
	v_mov_b32_e32 v221, v224
	v_pk_fma_f32 v[224:225], v[72:73], v[72:73], v[146:147] op_sel_hi:[1,1,0]
	s_nop 0
	v_mov_b32_e32 v225, v226
	v_pk_add_f32 v[220:221], v[220:221], v[224:225]
	s_nop 0
	v_pk_add_f32 v[218:219], v[218:219], v[220:221]
	s_nop 0
	v_add_f32_e32 v146, v218, v219
	ds_bpermute_b32 v209, v177, v146
	v_lshl_add_u64 v[218:219], v[222:223], 0, s[12:13]
	s_waitcnt lgkmcnt(0)
	v_add_f32_e32 v146, v146, v209
	ds_bpermute_b32 v209, v207, v146
	s_waitcnt lgkmcnt(0)
	v_add_f32_e32 v146, v146, v209
	v_fmamk_f32 v146, v146, 0x3c800000, v200
	v_rsq_f32_e32 v146, v146
	v_mul_f32_e32 v209, v42, v42
	v_pk_mul_f32 v[224:225], v[78:79], v[146:147] op_sel_hi:[1,0]
	v_pk_mul_f32 v[226:227], v[80:81], v[146:147] op_sel_hi:[1,0]
	v_pk_mul_f32 v[220:221], v[88:89], v[146:147] op_sel_hi:[1,0]
	v_pk_mul_f32 v[222:223], v[86:87], v[146:147] op_sel_hi:[1,0]
	v_pk_mul_f32 v[226:227], v[182:183], v[226:227]
	v_pk_mul_f32 v[224:225], v[184:185], v[224:225]
	v_pk_mul_f32 v[222:223], v[190:191], v[222:223]
	v_pk_mul_f32 v[220:221], v[178:179], v[220:221]
	v_pk_mul_f32 v[236:237], v[130:131], v[224:225]
	v_pk_mul_f32 v[238:239], v[132:133], v[226:227]
	v_pk_mul_f32 v[224:225], v[134:135], v[224:225]
	v_pk_mul_f32 v[226:227], v[136:137], v[226:227]
	v_pk_mul_f32 v[232:233], v[66:67], v[146:147] op_sel_hi:[1,0]
	v_pk_mul_f32 v[234:235], v[68:69], v[146:147] op_sel_hi:[1,0]
	v_pk_fma_f32 v[136:137], v[136:137], v[220:221], v[238:239] neg_lo:[0,0,1] neg_hi:[0,0,1]
	v_pk_fma_f32 v[220:221], v[132:133], v[220:221], v[226:227]
	v_pk_fma_f32 v[132:133], v[130:131], v[222:223], v[224:225]
	v_pk_mul_f32 v[228:229], v[72:73], v[146:147] op_sel_hi:[1,0]
	v_pk_mul_f32 v[230:231], v[70:71], v[146:147] op_sel_hi:[1,0]
	v_pk_mul_f32 v[234:235], v[186:187], v[234:235]
	v_pk_mul_f32 v[232:233], v[188:189], v[232:233]
	v_pk_fma_f32 v[134:135], v[134:135], v[222:223], v[236:237] neg_lo:[0,0,1] neg_hi:[0,0,1]
	v_pk_mul_f32 v[230:231], v[192:193], v[230:231]
	v_cvt_pk_bf16_f32 v130, v134, v135
	v_cvt_pk_bf16_f32 v131, v136, v137
	v_cvt_pk_bf16_f32 v132, v132, v133
	v_cvt_pk_bf16_f32 v133, v220, v221
	v_pk_mul_f32 v[228:229], v[180:181], v[228:229]
	global_store_dwordx4 v[218:219], v[130:133], off nt
	v_pk_mul_f32 v[220:221], v[60:61], v[60:61]
	v_pk_mul_f32 v[222:223], v[58:59], v[58:59]
	v_mul_f32_e32 v146, v51, v51
	s_waitcnt lgkmcnt(0)
; __device__ __forceinline__ unsigned cvt_pk_bf16(float lo, float hi) { unsigned r; asm volatile("v_cvt_pk_bf16_f32 %0, %1, %2" : "=v"(r) : "v"(lo), "v"(hi)); return r; }
;     __device__ __forceinline__ void operator()(const f32x4 (&acc)[2][2][4][2], const Unit& u, int wr, int wc, int fr, int fq) const {
;     ...
;         for (int ai = 0; ai < 2; ++ai) {
;             const int prow = prow_base + 2 * ai;
;             const f32x4 cr = *(const f32x4*)(cosT + prow * 16 + 4 * fq), sr = *(const f32x4*)(sinT + prow * 16 + 4 * fq);
; #pragma unroll
;             for (int m = 0; m < 4; ++m) {
;                 const int pcol = 16 * m + fr;
;                 const f32x4 cc = *(const f32x4*)(cosT + pcol * 16 + 4 * fq), sn = *(const f32x4*)(sinT + pcol * 16 + 4 * fq);
;                 float ss = 0.f;
; #pragma unroll
;                 for (int bj = 0; bj < 2; ++bj)
; #pragma unroll
;                     for (int n = 0; n < 2; ++n) { const f32x4 x = acc[ai][bj][m][n]; ss += (x[0] * x[0] + x[1] * x[1]) + (x[2] * x[2] + x[3] * x[3]); }
;                 ss += __shfl_xor(ss, 16); ss += __shfl_xor(ss, 32);
;                 const float rstd = __builtin_amdgcn_rsqf(ss * (1.0f / 64.0f) + RMS_EPS);
;                 bf16_t* rowp = base + (size_t)(ai * HALF + m * 16) * pitch;
; #pragma unroll
;                 for (int bj = 0; bj < 2; ++bj) { const f32x4 c = bj == 0 ? cr : cc, s = bj == 0 ? sr : sn;
;                     const f32x4 y0 = acc[ai][bj][m][0] * rstd * gv[bj][0], y1 = acc[ai][bj][m][1] * rstd * gv[bj][1];
;                     const f32x4 o0 = y0 * c - y1 * s, o1 = y1 * c + y0 * s;
;                     u32x4 w; w.x = cvt_pk_bf16(o0[0], o0[1]); w.y = cvt_pk_bf16(o0[2], o0[3]); w.z = cvt_pk_bf16(o1[0], o1[1]); w.w = cvt_pk_bf16(o1[2], o1[3]);
;                     *(u32x4*)(rowp + bj * 32) = w; }
	v_pk_mul_f32 v[130:131], v[210:211], v[232:233]
	v_pk_mul_f32 v[132:133], v[212:213], v[234:235]
	s_waitcnt lgkmcnt(0)
	v_pk_fma_f32 v[130:131], v[214:215], v[230:231], v[130:131] neg_lo:[0,0,1] neg_hi:[0,0,1]
	v_pk_fma_f32 v[132:133], v[216:217], v[228:229], v[132:133] neg_lo:[0,0,1] neg_hi:[0,0,1]
	v_pk_mul_f32 v[134:135], v[214:215], v[232:233]
	v_pk_mul_f32 v[136:137], v[216:217], v[234:235]
	v_pk_fma_f32 v[134:135], v[210:211], v[230:231], v[134:135]
	v_pk_fma_f32 v[136:137], v[212:213], v[228:229], v[136:137]
	v_cvt_pk_bf16_f32 v130, v130, v131
	v_cvt_pk_bf16_f32 v131, v132, v133
	v_cvt_pk_bf16_f32 v132, v134, v135
	v_pk_mul_f32 v[214:215], v[64:65], v[64:65]
	v_cvt_pk_bf16_f32 v133, v136, v137
	global_store_dwordx4 v[218:219], v[130:133], off offset:64 nt
	s_nop 1
	v_mov_b64 v[130:131], v[240:241]
	v_mov_b64 v[132:133], v[242:243]
	s_nop 0
	s_nop 1
	v_mov_b64 v[134:135], v[244:245]
	v_mov_b64 v[136:137], v[246:247]
	s_nop 0
	v_subrev_u32_e32 v252, s98, v156
	v_bfe_u32 v253, v252, 13, 1
	v_and_b32_e32 v252, 0xfff, v252
	v_lshl_or_b32 v252, v253, 12, v252
	v_add_u32_e32 v252, 0x20800, v252
	ds_read_b128 v[194:197], v252
	v_subrev_u32_e32 v252, s98, v154
	v_bfe_u32 v253, v252, 13, 1
	v_and_b32_e32 v252, 0xfff, v252
	v_lshl_or_b32 v252, v253, 12, v252
	v_add_u32_e32 v252, 0x20800, v252
	ds_read_b128 v[210:213], v252
	v_pk_mul_f32 v[216:217], v[62:63], v[62:63]
	v_mul_f32_e32 v224, v53, v53
	v_pk_mov_b32 v[226:227], v[216:217], v[214:215] op_sel:[1,0]
	v_mov_b32_e32 v217, v215
	v_pk_mov_b32 v[214:215], v[222:223], v[220:221] op_sel:[1,0]
	v_mov_b32_e32 v223, v221
	v_pk_add_f32 v[216:217], v[226:227], v[216:217]
	v_pk_add_f32 v[214:215], v[214:215], v[222:223]
	v_mul_f32_e32 v228, v43, v43
	v_mul_f32_e32 v229, v44, v44
	v_mul_f32_e32 v230, v45, v45
	v_pk_fma_f32 v[220:221], v[50:51], v[50:51], v[146:147] op_sel_hi:[1,1,0]
	v_pk_fma_f32 v[224:225], v[52:53], v[52:53], v[224:225] op_sel_hi:[1,1,0]
	v_pk_add_f32 v[216:217], v[216:217], v[216:217] op_sel:[0,1] op_sel_hi:[1,0]
	v_pk_add_f32 v[214:215], v[214:215], v[214:215] op_sel:[0,1] op_sel_hi:[1,0]
	v_mov_b32_e32 v221, v229
	v_mov_b32_e32 v225, v230
	v_mov_b32_e32 v217, v209
	v_mov_b32_e32 v215, v228
	v_pk_add_f32 v[220:221], v[220:221], v[224:225]
	v_pk_add_f32 v[214:215], v[216:217], v[214:215]
	v_lshl_add_u64 v[218:219], v[218:219], 0, s[0:1]
	v_pk_add_f32 v[214:215], v[214:215], v[220:221]
	s_nop 0
	v_add_f32_e32 v146, v214, v215
	ds_bpermute_b32 v209, v177, v146
	s_waitcnt lgkmcnt(0)
	v_add_f32_e32 v146, v146, v209
	ds_bpermute_b32 v209, v207, v146
	s_waitcnt lgkmcnt(0)
	v_add_f32_e32 v146, v146, v209
	v_fmamk_f32 v146, v146, 0x3c800000, v200
	v_rsq_f32_e32 v146, v146
	v_mul_f32_e32 v209, v27, v27
	v_pk_mul_f32 v[220:221], v[58:59], v[146:147] op_sel_hi:[1,0]
	v_pk_mul_f32 v[230:231], v[44:45], v[146:147] op_sel_hi:[1,0]
	v_pk_mul_f32 v[216:217], v[62:63], v[146:147] op_sel_hi:[1,0]
	v_pk_mul_f32 v[224:225], v[52:53], v[146:147] op_sel_hi:[1,0]
	v_pk_mul_f32 v[228:229], v[42:43], v[146:147] op_sel_hi:[1,0]
	v_pk_mul_f32 v[220:221], v[184:185], v[220:221]
	v_pk_mul_f32 v[230:231], v[186:187], v[230:231]
	v_pk_mul_f32 v[222:223], v[60:61], v[146:147] op_sel_hi:[1,0]
	v_pk_mul_f32 v[226:227], v[50:51], v[146:147] op_sel_hi:[1,0]
	v_pk_mul_f32 v[216:217], v[190:191], v[216:217]
	v_pk_mul_f32 v[224:225], v[180:181], v[224:225]
	v_pk_mul_f32 v[228:229], v[188:189], v[228:229]
	v_pk_mul_f32 v[214:215], v[64:65], v[146:147] op_sel_hi:[1,0]
	v_pk_mul_f32 v[222:223], v[182:183], v[222:223]
	v_pk_mul_f32 v[226:227], v[192:193], v[226:227]
	v_pk_mul_f32 v[214:215], v[178:179], v[214:215]
	v_mul_f32_e32 v146, v26, v26
	s_waitcnt lgkmcnt(0)
	v_pk_mul_f32 v[232:233], v[130:131], v[220:221]
	s_waitcnt lgkmcnt(0)
	v_pk_mul_f32 v[220:221], v[134:135], v[220:221]
	s_waitcnt lgkmcnt(0)
	v_pk_mul_f32 v[238:239], v[196:197], v[230:231]
	v_pk_mul_f32 v[236:237], v[194:195], v[228:229]
	s_waitcnt lgkmcnt(0)
	v_pk_mul_f32 v[228:229], v[210:211], v[228:229]
	v_pk_fma_f32 v[232:233], v[134:135], v[216:217], v[232:233] neg_lo:[0,0,1] neg_hi:[0,0,1]
	v_pk_fma_f32 v[216:217], v[130:131], v[216:217], v[220:221]
	v_pk_fma_f32 v[220:221], v[212:213], v[224:225], v[238:239] neg_lo:[0,0,1] neg_hi:[0,0,1]
	v_pk_mul_f32 v[212:213], v[212:213], v[230:231]
	v_pk_mul_f32 v[234:235], v[132:133], v[222:223]
	v_pk_mul_f32 v[222:223], v[136:137], v[222:223]
	v_pk_fma_f32 v[212:213], v[196:197], v[224:225], v[212:213]
	v_pk_fma_f32 v[196:197], v[194:195], v[226:227], v[228:229]
	v_pk_fma_f32 v[234:235], v[136:137], v[214:215], v[234:235] neg_lo:[0,0,1] neg_hi:[0,0,1]
	v_pk_fma_f32 v[222:223], v[132:133], v[214:215], v[222:223]
	v_pk_fma_f32 v[210:211], v[210:211], v[226:227], v[236:237] neg_lo:[0,0,1] neg_hi:[0,0,1]
	v_cvt_pk_bf16_f32 v214, v232, v233
	v_cvt_pk_bf16_f32 v215, v234, v235
	v_cvt_pk_bf16_f32 v216, v216, v217
	v_cvt_pk_bf16_f32 v217, v222, v223
	global_store_dwordx4 v[218:219], v[214:217], off nt
	v_cvt_pk_bf16_f32 v194, v210, v211
	v_cvt_pk_bf16_f32 v195, v220, v221
	v_cvt_pk_bf16_f32 v196, v196, v197
	v_cvt_pk_bf16_f32 v197, v212, v213
	global_store_dwordx4 v[218:219], v[194:197], off offset:64 nt
	v_subrev_u32_e32 v252, s98, v160
	v_bfe_u32 v253, v252, 13, 1
	v_and_b32_e32 v252, 0xfff, v252
	v_lshl_or_b32 v252, v253, 12, v252
	v_add_u32_e32 v252, 0x20800, v252
	ds_read_b128 v[194:197], v252
	s_nop 0
	v_subrev_u32_e32 v252, s98, v158
	v_bfe_u32 v253, v252, 13, 1
	v_and_b32_e32 v252, 0xfff, v252
	v_lshl_or_b32 v252, v253, 12, v252
	v_add_u32_e32 v252, 0x20800, v252
	ds_read_b128 v[210:213], v252
	v_pk_mul_f32 v[214:215], v[56:57], v[56:57]
	v_pk_mul_f32 v[216:217], v[54:55], v[54:55]
	v_lshl_add_u64 v[218:219], v[218:219], 0, s[12:13]
	v_pk_mov_b32 v[220:221], v[216:217], v[214:215] op_sel:[1,0]
	v_mov_b32_e32 v217, v215
	v_pk_add_f32 v[214:215], v[220:221], v[216:217]
	v_pk_mul_f32 v[216:217], v[48:49], v[48:49]
	v_pk_mul_f32 v[220:221], v[46:47], v[46:47]
	v_pk_add_f32 v[214:215], v[214:215], v[214:215] op_sel:[0,1] op_sel_hi:[1,0]
	v_pk_mov_b32 v[222:223], v[220:221], v[216:217] op_sel:[1,0]
	v_mov_b32_e32 v221, v217
	v_pk_add_f32 v[216:217], v[222:223], v[220:221]
	v_mov_b32_e32 v215, v146
	v_pk_add_f32 v[216:217], v[216:217], v[216:217] op_sel:[0,1] op_sel_hi:[1,0]
	v_mul_f32_e32 v146, v35, v35
	v_mov_b32_e32 v217, v209
	v_mul_f32_e32 v220, v28, v28
	v_pk_add_f32 v[214:215], v[214:215], v[216:217]
	v_pk_fma_f32 v[216:217], v[34:35], v[34:35], v[146:147] op_sel_hi:[1,1,0]
	v_mul_f32_e32 v146, v37, v37
	v_mul_f32_e32 v222, v29, v29
	v_mov_b32_e32 v217, v220
	v_pk_fma_f32 v[220:221], v[36:37], v[36:37], v[146:147] op_sel_hi:[1,1,0]
	s_nop 0
	v_mov_b32_e32 v221, v222
	v_pk_add_f32 v[216:217], v[216:217], v[220:221]
	s_nop 0
	v_pk_add_f32 v[214:215], v[214:215], v[216:217]
	s_nop 0
	v_add_f32_e32 v146, v214, v215
	ds_bpermute_b32 v209, v177, v146
	s_waitcnt lgkmcnt(0)
; __device__ __forceinline__ unsigned cvt_pk_bf16(float lo, float hi) { unsigned r; asm volatile("v_cvt_pk_bf16_f32 %0, %1, %2" : "=v"(r) : "v"(lo), "v"(hi)); return r; }
;     __device__ __forceinline__ void operator()(const f32x4 (&acc)[2][2][4][2], const Unit& u, int wr, int wc, int fr, int fq) const {
;     ...
;             for (int m = 0; m < 4; ++m) {
;                 const int pcol = 16 * m + fr;
;                 const f32x4 cc = *(const f32x4*)(cosT + pcol * 16 + 4 * fq), sn = *(const f32x4*)(sinT + pcol * 16 + 4 * fq);
;                 float ss = 0.f;
; #pragma unroll
;                 for (int bj = 0; bj < 2; ++bj)
; #pragma unroll
;                     for (int n = 0; n < 2; ++n) { const f32x4 x = acc[ai][bj][m][n]; ss += (x[0] * x[0] + x[1] * x[1]) + (x[2] * x[2] + x[3] * x[3]); }
;                 ss += __shfl_xor(ss, 16); ss += __shfl_xor(ss, 32);
;                 const float rstd = __builtin_amdgcn_rsqf(ss * (1.0f / 64.0f) + RMS_EPS);
;                 bf16_t* rowp = base + (size_t)(ai * HALF + m * 16) * pitch;
; #pragma unroll
;                 for (int bj = 0; bj < 2; ++bj) { const f32x4 c = bj == 0 ? cr : cc, s = bj == 0 ? sr : sn;
;                     const f32x4 y0 = acc[ai][bj][m][0] * rstd * gv[bj][0], y1 = acc[ai][bj][m][1] * rstd * gv[bj][1];
;                     const f32x4 o0 = y0 * c - y1 * s, o1 = y1 * c + y0 * s;
;                     u32x4 w; w.x = cvt_pk_bf16(o0[0], o0[1]); w.y = cvt_pk_bf16(o0[2], o0[3]); w.z = cvt_pk_bf16(o1[0], o1[1]); w.w = cvt_pk_bf16(o1[2], o1[3]);
;                     *(u32x4*)(rowp + bj * 32) = w; }
	v_add_f32_e32 v146, v146, v209
	ds_bpermute_b32 v209, v207, v146
	s_waitcnt lgkmcnt(0)
	v_add_f32_e32 v146, v146, v209
	v_fmamk_f32 v146, v146, 0x3c800000, v200
	v_rsq_f32_e32 v146, v146
	v_mul_f32_e32 v209, v10, v10
	v_pk_mul_f32 v[220:221], v[46:47], v[146:147] op_sel_hi:[1,0]
	v_pk_mul_f32 v[222:223], v[48:49], v[146:147] op_sel_hi:[1,0]
	v_pk_mul_f32 v[214:215], v[56:57], v[146:147] op_sel_hi:[1,0]
	v_pk_mul_f32 v[216:217], v[54:55], v[146:147] op_sel_hi:[1,0]
	v_pk_mul_f32 v[222:223], v[182:183], v[222:223]
	v_pk_mul_f32 v[220:221], v[184:185], v[220:221]
	v_pk_mul_f32 v[228:229], v[26:27], v[146:147] op_sel_hi:[1,0]
	v_pk_mul_f32 v[230:231], v[28:29], v[146:147] op_sel_hi:[1,0]
	v_pk_mul_f32 v[216:217], v[190:191], v[216:217]
	v_pk_mul_f32 v[214:215], v[178:179], v[214:215]
	v_pk_mul_f32 v[232:233], v[130:131], v[220:221]
	v_pk_mul_f32 v[234:235], v[132:133], v[222:223]
	v_pk_mul_f32 v[220:221], v[134:135], v[220:221]
	v_pk_mul_f32 v[222:223], v[136:137], v[222:223]
	v_pk_mul_f32 v[224:225], v[36:37], v[146:147] op_sel_hi:[1,0]
	v_pk_mul_f32 v[226:227], v[34:35], v[146:147] op_sel_hi:[1,0]
	v_pk_mul_f32 v[230:231], v[186:187], v[230:231]
	v_pk_mul_f32 v[228:229], v[188:189], v[228:229]
	v_pk_fma_f32 v[234:235], v[136:137], v[214:215], v[234:235] neg_lo:[0,0,1] neg_hi:[0,0,1]
	v_pk_fma_f32 v[232:233], v[134:135], v[216:217], v[232:233] neg_lo:[0,0,1] neg_hi:[0,0,1]
	v_pk_fma_f32 v[222:223], v[132:133], v[214:215], v[222:223]
	v_pk_fma_f32 v[216:217], v[130:131], v[216:217], v[220:221]
	v_cvt_pk_bf16_f32 v214, v232, v233
	v_cvt_pk_bf16_f32 v215, v234, v235
	v_pk_mul_f32 v[226:227], v[192:193], v[226:227]
	v_pk_mul_f32 v[224:225], v[180:181], v[224:225]
	v_cvt_pk_bf16_f32 v216, v216, v217
	v_cvt_pk_bf16_f32 v217, v222, v223
	global_store_dwordx4 v[218:219], v[214:217], off nt
	v_mul_f32_e32 v146, v19, v19
	s_waitcnt lgkmcnt(0)
	v_pk_mul_f32 v[220:221], v[210:211], v[228:229]
	v_pk_mul_f32 v[214:215], v[194:195], v[228:229]
	v_pk_mul_f32 v[222:223], v[212:213], v[230:231]
	v_pk_mul_f32 v[216:217], v[196:197], v[230:231]
	v_pk_fma_f32 v[210:211], v[210:211], v[226:227], v[214:215] neg_lo:[0,0,1] neg_hi:[0,0,1]
	v_pk_fma_f32 v[214:215], v[196:197], v[224:225], v[222:223]
	v_pk_fma_f32 v[196:197], v[194:195], v[226:227], v[220:221]
	v_pk_fma_f32 v[212:213], v[212:213], v[224:225], v[216:217] neg_lo:[0,0,1] neg_hi:[0,0,1]
	v_cvt_pk_bf16_f32 v194, v210, v211
	v_pk_mul_f32 v[216:217], v[38:39], v[38:39]
	v_cvt_pk_bf16_f32 v195, v212, v213
	v_cvt_pk_bf16_f32 v196, v196, v197
	v_cvt_pk_bf16_f32 v197, v214, v215
	global_store_dwordx4 v[218:219], v[194:197], off offset:64 nt
	v_subrev_u32_e32 v252, s98, v164
	v_bfe_u32 v253, v252, 13, 1
	v_and_b32_e32 v252, 0xfff, v252
	v_lshl_or_b32 v252, v253, 12, v252
	v_add_u32_e32 v252, 0x20800, v252
	ds_read_b128 v[194:197], v252
	s_nop 0
	v_subrev_u32_e32 v252, s98, v162
	v_bfe_u32 v253, v252, 13, 1
	v_and_b32_e32 v252, 0xfff, v252
	v_lshl_or_b32 v252, v253, 12, v252
	v_add_u32_e32 v252, 0x20800, v252
	ds_read_b128 v[210:213], v252
	v_pk_mul_f32 v[214:215], v[40:41], v[40:41]
	v_pk_mul_f32 v[220:221], v[32:33], v[32:33]
	v_pk_mul_f32 v[222:223], v[30:31], v[30:31]
	v_pk_mov_b32 v[226:227], v[216:217], v[214:215] op_sel:[1,0]
	v_mov_b32_e32 v217, v215
	v_pk_mov_b32 v[214:215], v[222:223], v[220:221] op_sel:[1,0]
	v_mov_b32_e32 v223, v221
	v_mul_f32_e32 v224, v21, v21
	v_pk_add_f32 v[216:217], v[226:227], v[216:217]
	v_pk_add_f32 v[214:215], v[214:215], v[222:223]
	v_mul_f32_e32 v228, v11, v11
	v_mul_f32_e32 v229, v12, v12
	v_mul_f32_e32 v230, v13, v13
	v_pk_fma_f32 v[220:221], v[18:19], v[18:19], v[146:147] op_sel_hi:[1,1,0]
	v_pk_fma_f32 v[224:225], v[20:21], v[20:21], v[224:225] op_sel_hi:[1,1,0]
	v_pk_add_f32 v[216:217], v[216:217], v[216:217] op_sel:[0,1] op_sel_hi:[1,0]
	v_pk_add_f32 v[214:215], v[214:215], v[214:215] op_sel:[0,1] op_sel_hi:[1,0]
	v_mov_b32_e32 v221, v229
	v_mov_b32_e32 v225, v230
	v_mov_b32_e32 v217, v209
	v_mov_b32_e32 v215, v228
	v_pk_add_f32 v[220:221], v[220:221], v[224:225]
	v_pk_add_f32 v[214:215], v[216:217], v[214:215]
	v_lshl_add_u64 v[218:219], v[218:219], 0, s[12:13]
	v_pk_add_f32 v[214:215], v[214:215], v[220:221]
	s_nop 0
	v_add_f32_e32 v146, v214, v215
	ds_bpermute_b32 v209, v177, v146
	s_waitcnt lgkmcnt(0)
	v_add_f32_e32 v146, v146, v209
	ds_bpermute_b32 v209, v207, v146
	s_waitcnt lgkmcnt(0)
	v_add_f32_e32 v146, v146, v209
	v_fmamk_f32 v146, v146, 0x3c800000, v200
	v_rsq_f32_e32 v146, v146
	v_mul_f32_e32 v209, v2, v2
	v_pk_mul_f32 v[220:221], v[30:31], v[146:147] op_sel_hi:[1,0]
	v_pk_mul_f32 v[222:223], v[32:33], v[146:147] op_sel_hi:[1,0]
	v_pk_mul_f32 v[214:215], v[40:41], v[146:147] op_sel_hi:[1,0]
	v_pk_mul_f32 v[216:217], v[38:39], v[146:147] op_sel_hi:[1,0]
	v_pk_mul_f32 v[222:223], v[182:183], v[222:223]
	v_pk_mul_f32 v[220:221], v[184:185], v[220:221]
	v_pk_mul_f32 v[228:229], v[10:11], v[146:147] op_sel_hi:[1,0]
	v_pk_mul_f32 v[230:231], v[12:13], v[146:147] op_sel_hi:[1,0]
	v_pk_mul_f32 v[216:217], v[190:191], v[216:217]
	v_pk_mul_f32 v[214:215], v[178:179], v[214:215]
	v_pk_mul_f32 v[232:233], v[130:131], v[220:221]
	v_pk_mul_f32 v[234:235], v[132:133], v[222:223]
	v_pk_mul_f32 v[220:221], v[134:135], v[220:221]
	v_pk_mul_f32 v[222:223], v[136:137], v[222:223]
	v_pk_mul_f32 v[224:225], v[20:21], v[146:147] op_sel_hi:[1,0]
	v_pk_mul_f32 v[226:227], v[18:19], v[146:147] op_sel_hi:[1,0]
	v_pk_mul_f32 v[230:231], v[186:187], v[230:231]
	v_pk_mul_f32 v[228:229], v[188:189], v[228:229]
	v_pk_fma_f32 v[234:235], v[136:137], v[214:215], v[234:235] neg_lo:[0,0,1] neg_hi:[0,0,1]
	v_pk_fma_f32 v[232:233], v[134:135], v[216:217], v[232:233] neg_lo:[0,0,1] neg_hi:[0,0,1]
	v_pk_fma_f32 v[222:223], v[132:133], v[214:215], v[222:223]
	v_pk_fma_f32 v[216:217], v[130:131], v[216:217], v[220:221]
	v_cvt_pk_bf16_f32 v214, v232, v233
	v_cvt_pk_bf16_f32 v215, v234, v235
	v_pk_mul_f32 v[226:227], v[192:193], v[226:227]
	v_pk_mul_f32 v[224:225], v[180:181], v[224:225]
	v_cvt_pk_bf16_f32 v216, v216, v217
	v_cvt_pk_bf16_f32 v217, v222, v223
	global_store_dwordx4 v[218:219], v[214:217], off nt
	v_mul_f32_e32 v146, v7, v7
	s_waitcnt lgkmcnt(0)
; __device__ __forceinline__ unsigned cvt_pk_bf16(float lo, float hi) { unsigned r; asm volatile("v_cvt_pk_bf16_f32 %0, %1, %2" : "=v"(r) : "v"(lo), "v"(hi)); return r; }
;     __device__ __forceinline__ void operator()(const f32x4 (&acc)[2][2][4][2], const Unit& u, int wr, int wc, int fr, int fq) const {
;     ...
;             for (int m = 0; m < 4; ++m) {
;                 const int pcol = 16 * m + fr;
;                 const f32x4 cc = *(const f32x4*)(cosT + pcol * 16 + 4 * fq), sn = *(const f32x4*)(sinT + pcol * 16 + 4 * fq);
;                 float ss = 0.f;
; #pragma unroll
;                 for (int bj = 0; bj < 2; ++bj)
; #pragma unroll
;                     for (int n = 0; n < 2; ++n) { const f32x4 x = acc[ai][bj][m][n]; ss += (x[0] * x[0] + x[1] * x[1]) + (x[2] * x[2] + x[3] * x[3]); }
;                 ss += __shfl_xor(ss, 16); ss += __shfl_xor(ss, 32);
;                 const float rstd = __builtin_amdgcn_rsqf(ss * (1.0f / 64.0f) + RMS_EPS);
;                 bf16_t* rowp = base + (size_t)(ai * HALF + m * 16) * pitch;
; #pragma unroll
;                 for (int bj = 0; bj < 2; ++bj) { const f32x4 c = bj == 0 ? cr : cc, s = bj == 0 ? sr : sn;
;                     const f32x4 y0 = acc[ai][bj][m][0] * rstd * gv[bj][0], y1 = acc[ai][bj][m][1] * rstd * gv[bj][1];
;                     const f32x4 o0 = y0 * c - y1 * s, o1 = y1 * c + y0 * s;
;                     u32x4 w; w.x = cvt_pk_bf16(o0[0], o0[1]); w.y = cvt_pk_bf16(o0[2], o0[3]); w.z = cvt_pk_bf16(o1[0], o1[1]); w.w = cvt_pk_bf16(o1[2], o1[3]);
;                     *(u32x4*)(rowp + bj * 32) = w; }
	v_pk_mul_f32 v[220:221], v[210:211], v[228:229]
	v_pk_mul_f32 v[214:215], v[194:195], v[228:229]
	v_pk_mul_f32 v[222:223], v[212:213], v[230:231]
	v_pk_mul_f32 v[216:217], v[196:197], v[230:231]
	v_pk_fma_f32 v[210:211], v[210:211], v[226:227], v[214:215] neg_lo:[0,0,1] neg_hi:[0,0,1]
	v_pk_fma_f32 v[214:215], v[196:197], v[224:225], v[222:223]
	v_pk_fma_f32 v[196:197], v[194:195], v[226:227], v[220:221]
	v_pk_fma_f32 v[212:213], v[212:213], v[224:225], v[216:217] neg_lo:[0,0,1] neg_hi:[0,0,1]
	v_cvt_pk_bf16_f32 v194, v210, v211
	v_pk_mul_f32 v[216:217], v[22:23], v[22:23]
	v_cvt_pk_bf16_f32 v195, v212, v213
	v_cvt_pk_bf16_f32 v196, v196, v197
	v_cvt_pk_bf16_f32 v197, v214, v215
	global_store_dwordx4 v[218:219], v[194:197], off offset:64 nt
	v_subrev_u32_e32 v252, s98, v168
	v_bfe_u32 v253, v252, 13, 1
	v_and_b32_e32 v252, 0xfff, v252
	v_lshl_or_b32 v252, v253, 12, v252
	v_add_u32_e32 v252, 0x20800, v252
	ds_read_b128 v[194:197], v252
	s_nop 0
	v_subrev_u32_e32 v252, s98, v166
	v_bfe_u32 v253, v252, 13, 1
	v_and_b32_e32 v252, 0xfff, v252
	v_lshl_or_b32 v252, v253, 12, v252
	v_add_u32_e32 v252, 0x20800, v252
	ds_read_b128 v[210:213], v252
	v_pk_mul_f32 v[214:215], v[24:25], v[24:25]
	v_pk_mul_f32 v[220:221], v[16:17], v[16:17]
	v_pk_mul_f32 v[222:223], v[14:15], v[14:15]
	v_pk_mov_b32 v[226:227], v[216:217], v[214:215] op_sel:[1,0]
	v_mov_b32_e32 v217, v215
	v_pk_mov_b32 v[214:215], v[222:223], v[220:221] op_sel:[1,0]
	v_mov_b32_e32 v223, v221
	v_mul_f32_e32 v224, v9, v9
	v_pk_add_f32 v[216:217], v[226:227], v[216:217]
	v_pk_add_f32 v[214:215], v[214:215], v[222:223]
	v_mul_f32_e32 v228, v3, v3
	v_mul_f32_e32 v229, v4, v4
	v_mul_f32_e32 v230, v5, v5
	v_pk_fma_f32 v[220:221], v[6:7], v[6:7], v[146:147] op_sel_hi:[1,1,0]
	v_pk_fma_f32 v[224:225], v[8:9], v[8:9], v[224:225] op_sel_hi:[1,1,0]
	v_pk_add_f32 v[216:217], v[216:217], v[216:217] op_sel:[0,1] op_sel_hi:[1,0]
	v_pk_add_f32 v[214:215], v[214:215], v[214:215] op_sel:[0,1] op_sel_hi:[1,0]
	v_mov_b32_e32 v221, v229
	v_mov_b32_e32 v225, v230
	v_mov_b32_e32 v217, v209
	v_mov_b32_e32 v215, v228
	v_pk_add_f32 v[220:221], v[220:221], v[224:225]
	v_pk_add_f32 v[214:215], v[216:217], v[214:215]
	s_nop 0
	v_pk_add_f32 v[214:215], v[214:215], v[220:221]
	s_nop 0
	v_add_f32_e32 v146, v214, v215
	ds_bpermute_b32 v177, v177, v146
	v_lshl_add_u64 v[214:215], v[218:219], 0, s[12:13]
	s_waitcnt lgkmcnt(0)
	v_add_f32_e32 v146, v146, v177
	ds_bpermute_b32 v177, v207, v146
	s_waitcnt lgkmcnt(0)
	v_add_f32_e32 v146, v146, v177
	v_fmamk_f32 v146, v146, 0x3c800000, v200
	v_rsq_f32_e32 v146, v146
	s_nop 0
	v_pk_mul_f32 v[220:221], v[14:15], v[146:147] op_sel_hi:[1,0]
	v_pk_mul_f32 v[222:223], v[16:17], v[146:147] op_sel_hi:[1,0]
	v_pk_mul_f32 v[216:217], v[24:25], v[146:147] op_sel_hi:[1,0]
	v_pk_mul_f32 v[218:219], v[22:23], v[146:147] op_sel_hi:[1,0]
	v_pk_mul_f32 v[182:183], v[182:183], v[222:223]
	v_pk_mul_f32 v[184:185], v[184:185], v[220:221]
	v_pk_mul_f32 v[190:191], v[190:191], v[218:219]
	v_pk_mul_f32 v[178:179], v[178:179], v[216:217]
	v_pk_mul_f32 v[216:217], v[130:131], v[184:185]
	v_pk_mul_f32 v[218:219], v[132:133], v[182:183]
	v_pk_mul_f32 v[184:185], v[134:135], v[184:185]
	v_pk_mul_f32 v[182:183], v[136:137], v[182:183]
	v_pk_mul_f32 v[228:229], v[2:3], v[146:147] op_sel_hi:[1,0]
	v_pk_mul_f32 v[230:231], v[4:5], v[146:147] op_sel_hi:[1,0]
	v_pk_fma_f32 v[136:137], v[136:137], v[178:179], v[218:219] neg_lo:[0,0,1] neg_hi:[0,0,1]
	v_pk_fma_f32 v[178:179], v[132:133], v[178:179], v[182:183]
	v_pk_fma_f32 v[132:133], v[130:131], v[190:191], v[184:185]
	v_pk_mul_f32 v[224:225], v[8:9], v[146:147] op_sel_hi:[1,0]
	v_pk_mul_f32 v[226:227], v[6:7], v[146:147] op_sel_hi:[1,0]
	v_pk_mul_f32 v[186:187], v[186:187], v[230:231]
	v_pk_mul_f32 v[188:189], v[188:189], v[228:229]
	v_pk_fma_f32 v[134:135], v[134:135], v[190:191], v[216:217] neg_lo:[0,0,1] neg_hi:[0,0,1]
	v_pk_mul_f32 v[192:193], v[192:193], v[226:227]
	v_cvt_pk_bf16_f32 v130, v134, v135
	v_cvt_pk_bf16_f32 v131, v136, v137
	v_cvt_pk_bf16_f32 v132, v132, v133
	v_cvt_pk_bf16_f32 v133, v178, v179
	v_pk_mul_f32 v[180:181], v[180:181], v[224:225]
	global_store_dwordx4 v[214:215], v[130:133], off nt
	s_waitcnt lgkmcnt(0)
	v_pk_mul_f32 v[134:135], v[210:211], v[188:189]
	v_pk_mul_f32 v[130:131], v[194:195], v[188:189]
	v_pk_mul_f32 v[132:133], v[196:197], v[186:187]
	v_pk_mul_f32 v[136:137], v[212:213], v[186:187]
	v_pk_fma_f32 v[132:133], v[212:213], v[180:181], v[132:133] neg_lo:[0,0,1] neg_hi:[0,0,1]
	v_pk_fma_f32 v[130:131], v[210:211], v[192:193], v[130:131] neg_lo:[0,0,1] neg_hi:[0,0,1]
	v_pk_fma_f32 v[136:137], v[196:197], v[180:181], v[136:137]
	v_pk_fma_f32 v[134:135], v[194:195], v[192:193], v[134:135]
	v_cvt_pk_bf16_f32 v130, v130, v131
	v_cvt_pk_bf16_f32 v131, v132, v133
	s_nop 0
	v_cvt_pk_bf16_f32 v132, v134, v135
	v_cvt_pk_bf16_f32 v133, v136, v137
	global_store_dwordx4 v[214:215], v[130:133], off offset:64 nt

; __device__ __forceinline__ unsigned cvt_pk_bf16(float lo, float hi) { unsigned r; asm volatile("v_cvt_pk_bf16_f32 %0, %1, %2" : "=v"(r) : "v"(lo), "v"(hi)); return r; }
;     __device__ __forceinline__ void operator()(const f32x4 (&acc)[2][2][4][2], const Unit& u, int wr, int wc, int fr, int fq) const {
;     ...
;         if (u.pn >= 3 || (u.pn == 2 && wc >= 2)) {
;             bf16_t* base; int pitch;
;             if (u.pn >= 3) { base = U + (size_t)row0 * 512 + (u.pn - 3) * 256 + wc * 32 + 8 * fq; pitch = 512; }
;             else { base = KV + (size_t)row0 * 256 + 128 + (wc - 2) * 64 + 8 * fq; pitch = 256; }
;             const int bjs = (u.pn >= 3) ? HALF : 32;
; #pragma unroll
;             for (int ai = 0; ai < 2; ++ai)
; #pragma unroll
;                 for (int m = 0; m < 4; ++m) { bf16_t* rowp = base + (size_t)(ai * HALF + m * 16) * pitch;
; #pragma unroll
;                     for (int bj = 0; bj < 2; ++bj) { const f32x4 v0 = acc[ai][bj][m][0], v1 = acc[ai][bj][m][1];
;                         u32x4 w; w.x = cvt_pk_bf16(v0[0], v0[1]); w.y = cvt_pk_bf16(v0[2], v0[3]); w.z = cvt_pk_bf16(v1[0], v1[1]); w.w = cvt_pk_bf16(v1[2], v1[3]);
;                         *(u32x4*)(rowp + bj * bjs) = w; } }
;             return;
.LBB0_262:
	s_lshl_b32 s0, s84, s12
	s_lshl_b32 s12, s0, 1
	v_lshl_add_u64 v[130:131], v[130:131], 0, s[12:13]
	v_lshlrev_b32_e32 v146, 1, v148
	s_lshl_b32 s0, 1, s19
	v_lshl_add_u64 v[130:131], v[130:131], 0, v[146:147]
	s_lshl_b32 s12, s0, 1
	v_cvt_pk_bf16_f32 v126, v126, v127
	v_cvt_pk_bf16_f32 v127, v128, v129
	v_cvt_pk_bf16_f32 v128, v122, v123
	v_cvt_pk_bf16_f32 v129, v124, v125
	global_store_dwordx4 v[130:131], v[126:129], off nt
	v_cvt_pk_bf16_f32 v118, v118, v119
	v_cvt_pk_bf16_f32 v119, v120, v121
	v_cvt_pk_bf16_f32 v120, v110, v111
	v_lshl_add_u64 v[110:111], v[130:131], 0, s[12:13]
	s_lshl_b32 s28, s30, 5
	s_mov_b32 s29, s13
	v_cvt_pk_bf16_f32 v121, v112, v113
	global_store_dwordx4 v[110:111], v[118:121], off nt
	v_cvt_pk_bf16_f32 v110, v114, v115
	v_cvt_pk_bf16_f32 v111, v116, v117
	v_cvt_pk_bf16_f32 v112, v106, v107
	v_cvt_pk_bf16_f32 v113, v108, v109
	s_mul_i32 s0, s30, 0xa0
	s_nop 0
	v_lshl_add_u64 v[118:119], v[130:131], 0, s[28:29]
	global_store_dwordx4 v[118:119], v[110:113], off nt
	v_cvt_pk_bf16_f32 v98, v98, v99
	v_cvt_pk_bf16_f32 v99, v100, v101
	v_cvt_pk_bf16_f32 v100, v90, v91
	v_lshl_add_u64 v[90:91], v[118:119], 0, s[12:13]
	v_cvt_pk_bf16_f32 v101, v92, v93
	global_store_dwordx4 v[90:91], v[98:101], off nt
	v_cvt_pk_bf16_f32 v90, v102, v103
	v_cvt_pk_bf16_f32 v91, v104, v105
	v_cvt_pk_bf16_f32 v92, v94, v95
	v_cvt_pk_bf16_f32 v93, v96, v97
	s_mov_b32 s1, s13
	s_nop 0
	v_lshl_add_u64 v[98:99], v[118:119], 0, s[28:29]
	global_store_dwordx4 v[98:99], v[90:93], off nt
	v_cvt_pk_bf16_f32 v82, v82, v83
	v_cvt_pk_bf16_f32 v83, v84, v85
	v_cvt_pk_bf16_f32 v84, v74, v75
	v_lshl_add_u64 v[74:75], v[98:99], 0, s[12:13]
	v_cvt_pk_bf16_f32 v85, v76, v77
	global_store_dwordx4 v[74:75], v[82:85], off nt
	v_cvt_pk_bf16_f32 v74, v86, v87
	v_cvt_pk_bf16_f32 v75, v88, v89
	v_cvt_pk_bf16_f32 v76, v78, v79
	v_cvt_pk_bf16_f32 v77, v80, v81
	s_nop 1
	v_lshl_add_u64 v[82:83], v[98:99], 0, s[28:29]
	global_store_dwordx4 v[82:83], v[74:77], off nt
	v_cvt_pk_bf16_f32 v70, v70, v71
	v_cvt_pk_bf16_f32 v71, v72, v73
	v_cvt_pk_bf16_f32 v72, v66, v67
	v_lshl_add_u64 v[66:67], v[82:83], 0, s[12:13]
	v_cvt_pk_bf16_f32 v73, v68, v69
	global_store_dwordx4 v[66:67], v[70:73], off nt
	v_lshl_add_u64 v[66:67], v[82:83], 0, s[0:1]
	v_cvt_pk_bf16_f32 v62, v62, v63
	v_cvt_pk_bf16_f32 v63, v64, v65
	v_cvt_pk_bf16_f32 v64, v58, v59
	v_cvt_pk_bf16_f32 v65, v60, v61
	global_store_dwordx4 v[66:67], v[62:65], off nt
	v_cvt_pk_bf16_f32 v50, v50, v51
	v_cvt_pk_bf16_f32 v51, v52, v53
	v_cvt_pk_bf16_f32 v52, v42, v43
	v_lshl_add_u64 v[42:43], v[66:67], 0, s[12:13]
	v_cvt_pk_bf16_f32 v53, v44, v45
	global_store_dwordx4 v[42:43], v[50:53], off nt
	v_cvt_pk_bf16_f32 v42, v54, v55
	v_cvt_pk_bf16_f32 v43, v56, v57
	v_cvt_pk_bf16_f32 v44, v46, v47
	v_cvt_pk_bf16_f32 v45, v48, v49
	s_nop 1
	v_lshl_add_u64 v[50:51], v[66:67], 0, s[28:29]
	global_store_dwordx4 v[50:51], v[42:45], off nt
	v_cvt_pk_bf16_f32 v34, v34, v35
	v_cvt_pk_bf16_f32 v35, v36, v37
	v_cvt_pk_bf16_f32 v36, v26, v27
	v_lshl_add_u64 v[26:27], v[50:51], 0, s[12:13]
	v_cvt_pk_bf16_f32 v37, v28, v29
	global_store_dwordx4 v[26:27], v[34:37], off nt
	v_cvt_pk_bf16_f32 v26, v38, v39
	v_cvt_pk_bf16_f32 v27, v40, v41
	v_cvt_pk_bf16_f32 v28, v30, v31
	v_cvt_pk_bf16_f32 v29, v32, v33
	s_nop 1
	v_lshl_add_u64 v[34:35], v[50:51], 0, s[28:29]
	global_store_dwordx4 v[34:35], v[26:29], off nt
	v_cvt_pk_bf16_f32 v18, v18, v19
	v_cvt_pk_bf16_f32 v19, v20, v21
	v_cvt_pk_bf16_f32 v20, v10, v11
	v_lshl_add_u64 v[10:11], v[34:35], 0, s[12:13]
	v_cvt_pk_bf16_f32 v21, v12, v13
	global_store_dwordx4 v[10:11], v[18:21], off nt
	v_cvt_pk_bf16_f32 v10, v22, v23
	v_cvt_pk_bf16_f32 v11, v24, v25
	v_cvt_pk_bf16_f32 v12, v14, v15
	v_cvt_pk_bf16_f32 v13, v16, v17
	s_nop 1
	v_lshl_add_u64 v[18:19], v[34:35], 0, s[28:29]
	global_store_dwordx4 v[18:19], v[10:13], off nt
	v_cvt_pk_bf16_f32 v6, v6, v7
	v_cvt_pk_bf16_f32 v7, v8, v9
	v_cvt_pk_bf16_f32 v8, v2, v3
	v_lshl_add_u64 v[2:3], v[18:19], 0, s[12:13]
	v_cvt_pk_bf16_f32 v9, v4, v5
	global_store_dwordx4 v[2:3], v[6:9], off nt
